# WIN phase: permute tile-to-CU assignment (4-cycle of pn 4,5,10,19) to balance epilogue cost across CU types
# speedup vs baseline: 1.0141x; 1.0063x over previous
.LBB0_402:
	s_cmp_eq_u32 s56, 4
	s_cselect_b32 s60, 19, s56
	s_cmp_eq_u32 s56, 5
	s_cselect_b32 s60, 4, s60
	s_cmp_eq_u32 s56, 10
	s_cselect_b32 s60, 5, s60
	s_cmp_eq_u32 s56, 19
	s_cselect_b32 s56, 10, s60
	s_ashr_i32 s59, s58, 31
	s_lshl_b64 s[60:61], s[58:59], 19
	s_add_u32 s60, s14, s60
	s_addc_u32 s61, s15, s61
	s_and_b64 s[62:63], s[36:37], exec
	s_cselect_b32 s59, s61, s67
	s_cselect_b32 s70, s60, s66
	s_ashr_i32 s57, s56, 31
	s_lshl_b64 s[62:63], s[56:57], 19
	s_add_u32 s62, s2, s62
	s_addc_u32 s63, s3, s63
	s_and_b64 s[68:69], s[36:37], exec
	s_cselect_b32 s57, s63, s65
	s_cselect_b32 s71, s62, s64
	s_add_u32 s72, s64, 0x100
	s_addc_u32 s73, s65, 0
	s_add_u32 s64, s66, 0x40080
	v_mov_b32_e32 v2, 0
	s_addc_u32 s65, s67, 0
	s_mov_b32 s74, -2
	v_mov_b32_e32 v3, v2
	v_mov_b32_e32 v4, v2
	v_mov_b32_e32 v5, v2
	v_mov_b32_e32 v6, v2
	v_mov_b32_e32 v7, v2
	v_mov_b32_e32 v8, v2
	v_mov_b32_e32 v9, v2
	v_mov_b32_e32 v10, v2
	v_mov_b32_e32 v11, v2
	v_mov_b32_e32 v12, v2
	v_mov_b32_e32 v13, v2
	v_mov_b32_e32 v14, v2
	v_mov_b32_e32 v15, v2
	v_mov_b32_e32 v16, v2
	v_mov_b32_e32 v17, v2
	v_mov_b32_e32 v18, v2
	v_mov_b32_e32 v19, v2
	v_mov_b32_e32 v20, v2
	v_mov_b32_e32 v21, v2
	v_mov_b32_e32 v22, v2
	v_mov_b32_e32 v23, v2
	v_mov_b32_e32 v24, v2
	v_mov_b32_e32 v25, v2
	v_mov_b32_e32 v26, v2
	v_mov_b32_e32 v27, v2
	v_mov_b32_e32 v28, v2
	v_mov_b32_e32 v29, v2
	v_mov_b32_e32 v30, v2
	v_mov_b32_e32 v31, v2
	v_mov_b32_e32 v32, v2
	v_mov_b32_e32 v33, v2
	v_mov_b32_e32 v66, v2
	v_mov_b32_e32 v67, v2
	v_mov_b32_e32 v68, v2
	v_mov_b32_e32 v69, v2
	v_mov_b32_e32 v70, v2
	v_mov_b32_e32 v71, v2
	v_mov_b32_e32 v72, v2
	v_mov_b32_e32 v73, v2
	v_mov_b32_e32 v74, v2
	v_mov_b32_e32 v75, v2
	v_mov_b32_e32 v76, v2
	v_mov_b32_e32 v77, v2
	v_mov_b32_e32 v78, v2
	v_mov_b32_e32 v79, v2
	v_mov_b32_e32 v80, v2
	v_mov_b32_e32 v81, v2
	v_mov_b32_e32 v82, v2
	v_mov_b32_e32 v83, v2
	v_mov_b32_e32 v84, v2
	v_mov_b32_e32 v85, v2
	v_mov_b32_e32 v86, v2
	v_mov_b32_e32 v87, v2
	v_mov_b32_e32 v88, v2
	v_mov_b32_e32 v89, v2
	v_mov_b32_e32 v90, v2
	v_mov_b32_e32 v91, v2
	v_mov_b32_e32 v92, v2
	v_mov_b32_e32 v93, v2
	v_mov_b32_e32 v98, v2
	v_mov_b32_e32 v99, v2
	v_mov_b32_e32 v100, v2
	v_mov_b32_e32 v101, v2
	v_mov_b32_e32 v34, v2
	v_mov_b32_e32 v35, v2
	v_mov_b32_e32 v36, v2
	v_mov_b32_e32 v37, v2
	v_mov_b32_e32 v38, v2
	v_mov_b32_e32 v39, v2
	v_mov_b32_e32 v40, v2
	v_mov_b32_e32 v41, v2
	v_mov_b32_e32 v42, v2
	v_mov_b32_e32 v43, v2
	v_mov_b32_e32 v44, v2
	v_mov_b32_e32 v45, v2
	v_mov_b32_e32 v46, v2
	v_mov_b32_e32 v47, v2
	v_mov_b32_e32 v48, v2
	v_mov_b32_e32 v49, v2
	v_mov_b32_e32 v50, v2
	v_mov_b32_e32 v51, v2
	v_mov_b32_e32 v52, v2
	v_mov_b32_e32 v53, v2
	v_mov_b32_e32 v54, v2
	v_mov_b32_e32 v55, v2
	v_mov_b32_e32 v56, v2
	v_mov_b32_e32 v57, v2
	v_mov_b32_e32 v58, v2
	v_mov_b32_e32 v59, v2
	v_mov_b32_e32 v60, v2
	v_mov_b32_e32 v61, v2
	v_mov_b32_e32 v62, v2
	v_mov_b32_e32 v63, v2
	v_mov_b32_e32 v64, v2
	v_mov_b32_e32 v65, v2
	v_mov_b32_e32 v102, v2
	v_mov_b32_e32 v103, v2
	v_mov_b32_e32 v104, v2
	v_mov_b32_e32 v105, v2
	v_mov_b32_e32 v106, v2
	v_mov_b32_e32 v107, v2
	v_mov_b32_e32 v108, v2
	v_mov_b32_e32 v109, v2
	v_mov_b32_e32 v110, v2
	v_mov_b32_e32 v111, v2
	v_mov_b32_e32 v112, v2
	v_mov_b32_e32 v113, v2
	v_mov_b32_e32 v114, v2
	v_mov_b32_e32 v115, v2
	v_mov_b32_e32 v116, v2
	v_mov_b32_e32 v117, v2
	v_mov_b32_e32 v118, v2
	v_mov_b32_e32 v119, v2
	v_mov_b32_e32 v120, v2
	v_mov_b32_e32 v121, v2
	v_mov_b32_e32 v122, v2
	v_mov_b32_e32 v123, v2
	v_mov_b32_e32 v124, v2
	v_mov_b32_e32 v125, v2
	v_mov_b32_e32 v126, v2
	v_mov_b32_e32 v127, v2
	v_mov_b32_e32 v128, v2
	v_mov_b32_e32 v129, v2
	v_mov_b32_e32 v130, v2
	v_mov_b32_e32 v131, v2
	v_mov_b32_e32 v132, v2
	v_mov_b32_e32 v133, v2
